# NSA stagger + per-cluster s_setprio raises neutralised in the selected/window loops (so the partner wave's softmax VALU is not starved during the other wave's MFMA clusters)
# baseline (speedup 1.0000x reference)
; #define LAS __attribute__((address_space(3)))
; #define MFMA32(a, b, c) __builtin_amdgcn_mfma_f32_32x32x16_bf16((a), (b), (c), 0, 0, 0)
; #define SBAR() __builtin_amdgcn_sched_barrier(0)
; template <int KSTR> DI void qk64b(f32x16& s0, f32x16& s1, const lds8* kp, const bf16x8 (&q)[4], float bias) {
;   bf16x8 a[8];
; #pragma unroll
;   for (int ks = 0; ks < 4; ++ks) { a[2 * ks] = *(const LAS bf16x8*)(kp + ks * 32); a[2 * ks + 1] = *(const LAS bf16x8*)(kp + 32 * KSTR + ks * 32); }
; #pragma unroll
;   for (int i = 0; i < 16; ++i) { s0[i] = bias; s1[i] = bias; }
;   SBAR();
;   __builtin_amdgcn_s_setprio(1);
; #pragma unroll
;   for (int ks = 0; ks < 4; ++ks) { s0 = MFMA32(a[2 * ks], q[ks], s0); s1 = MFMA32(a[2 * ks + 1], q[ks], s1); }
;   __builtin_amdgcn_s_setprio(0);
;   SBAR();
; }
; template <int MODE, int SLOT> DI void ns_valu(volatile LAS int* jl, int t, int ntl, int qpos, int h, int blk, f32x16& s0, f32x16& s1, f32x16& du0, f32x16& du1, f32x16 (&O)[2], float& muse, float& l, bf16x8 (&P)[4], CmpCap& cap) {
;     ...
;       } else if (MODE == 1) {
;         if (j == blk) {
;           const int lim = qpos - 64 * j - 4 * h;
; #pragma unroll
;           for (int i = 0; i < 16; ++i) { const int ci = (i & 3) + 8 * (i >> 2); if (ci > lim) s0[i] = NEG; if (ci + 32 > lim) s1[i] = NEG; }
;         }
.LBB0_940:
	s_mul_i32 s94, s6, 0x4800
	s_add_i32 s95, s94, 0
	v_mov_b32_e32 v139, s90
	v_add_u32_e32 v33, s95, v213
	ds_read_b32 v32, v139
	ds_read_b128 v[96:99], v33 offset:4608
	ds_read_b128 v[100:103], v33
	ds_read_b128 v[104:107], v33 offset:32
	ds_read_b128 v[108:111], v33 offset:4640
	ds_read_b128 v[112:115], v33 offset:64
	ds_read_b128 v[116:119], v33 offset:4672
	ds_read_b128 v[120:123], v33 offset:96
	ds_read_b128 v[124:127], v33 offset:4704
	s_waitcnt lgkmcnt(8)
	v_readfirstlane_b32 s84, v32
	s_nop 1
	v_lshrrev_b32_e32 v32, s84, v137
	v_and_b32_e32 v32, 1, v32
	v_cmp_eq_u32_e32 vcc, 1, v32
	s_nop 1
	v_cndmask_b32_e64 v32, v207, -v138, vcc
	v_mov_b32_e32 v33, v32
	v_mov_b32_e32 v34, v32
	v_mov_b32_e32 v35, v32
	v_mov_b32_e32 v36, v32
	v_mov_b32_e32 v37, v32
	v_mov_b32_e32 v38, v32
	v_mov_b32_e32 v39, v32
	v_mov_b32_e32 v40, v32
	v_mov_b32_e32 v41, v32
	v_mov_b32_e32 v42, v32
	v_mov_b32_e32 v43, v32
	v_mov_b32_e32 v44, v32
	v_mov_b32_e32 v45, v32
	v_mov_b32_e32 v46, v32
	v_mov_b32_e32 v47, v32
	s_setprio 0
	s_waitcnt lgkmcnt(6)
	v_mfma_f32_32x32x16_bf16 v[48:63], v[100:103], v[160:163], v[32:47]
	v_mfma_f32_32x32x16_bf16 v[32:47], v[96:99], v[160:163], v[32:47]
	s_waitcnt lgkmcnt(5)
	v_mfma_f32_32x32x16_bf16 v[48:63], v[104:107], v[168:171], v[48:63]
	s_waitcnt lgkmcnt(4)
	v_mfma_f32_32x32x16_bf16 v[32:47], v[108:111], v[168:171], v[32:47]
	s_waitcnt lgkmcnt(3)
	v_mfma_f32_32x32x16_bf16 v[48:63], v[112:115], v[164:167], v[48:63]
	s_waitcnt lgkmcnt(2)
	v_mfma_f32_32x32x16_bf16 v[32:47], v[116:119], v[164:167], v[32:47]
	s_waitcnt lgkmcnt(1)
	v_mfma_f32_32x32x16_bf16 v[48:63], v[120:123], v[172:175], v[48:63]
	s_waitcnt lgkmcnt(0)
	v_mfma_f32_32x32x16_bf16 v[32:47], v[124:127], v[172:175], v[32:47]
	s_setprio 0
	s_cmp_lg_u32 s84, s77
	s_cbranch_scc1 .LBB0_944
	s_and_b64 vcc, s[70:71], s[66:67]
	s_nop 7
	v_cndmask_b32_e32 v45, v45, v207, vcc
	s_and_b64 vcc, vcc, s[62:63]
	v_cndmask_b32_e32 v44, v44, v207, vcc
	s_and_b64 vcc, vcc, s[58:59]
	v_cndmask_b32_e32 v43, v43, v207, vcc
	s_and_b64 vcc, vcc, s[54:55]
	v_cndmask_b32_e32 v42, v42, v207, vcc
	s_and_b64 vcc, vcc, s[50:51]
	v_cndmask_b32_e32 v41, v41, v207, vcc
	s_and_b64 vcc, vcc, s[46:47]
	v_cndmask_b32_e32 v40, v40, v207, vcc
	s_and_b64 vcc, vcc, s[42:43]
	v_cndmask_b32_e32 v39, v39, v207, vcc
	s_and_b64 vcc, vcc, s[38:39]
	v_cndmask_b32_e32 v38, v38, v207, vcc
	s_and_b64 vcc, vcc, s[34:35]
	v_cndmask_b32_e32 v37, v37, v207, vcc
	s_and_b64 vcc, vcc, s[28:29]
	v_cndmask_b32_e32 v36, v36, v207, vcc
	s_and_b64 vcc, vcc, s[24:25]
	v_cndmask_b32_e32 v35, v35, v207, vcc
	s_and_b64 vcc, vcc, s[20:21]
	v_cndmask_b32_e32 v34, v34, v207, vcc
	s_and_b64 vcc, vcc, s[16:17]
	v_cndmask_b32_e32 v33, v33, v207, vcc
	s_and_b64 vcc, vcc, s[12:13]
	v_cndmask_b32_e64 v46, v46, v207, s[70:71]
	v_cndmask_b32_e32 v32, v32, v207, vcc
	s_and_saveexec_b64 s[84:85], s[74:75]
	s_mov_b32 s86, 0xf149f2ca
	v_mov_b32_e32 v47, s86
	s_or_b64 exec, exec, s[84:85]
	s_and_b64 vcc, s[72:73], s[68:69]
	v_cndmask_b32_e32 v62, v62, v207, vcc
	s_and_b64 vcc, vcc, s[64:65]
	v_cndmask_b32_e32 v61, v61, v207, vcc
	s_and_b64 vcc, vcc, s[60:61]
	v_cndmask_b32_e32 v60, v60, v207, vcc
	s_and_b64 vcc, vcc, s[56:57]
	v_cndmask_b32_e32 v59, v59, v207, vcc
	s_and_b64 vcc, vcc, s[52:53]
	v_cndmask_b32_e32 v58, v58, v207, vcc
	s_and_b64 vcc, vcc, s[48:49]
	v_cndmask_b32_e32 v57, v57, v207, vcc
	s_and_b64 vcc, vcc, s[44:45]
	v_cndmask_b32_e32 v56, v56, v207, vcc
	s_and_b64 vcc, vcc, s[40:41]
	v_cndmask_b32_e32 v55, v55, v207, vcc
	s_and_b64 vcc, vcc, s[36:37]
	v_cndmask_b32_e32 v54, v54, v207, vcc
	s_and_b64 vcc, vcc, s[30:31]
	v_cndmask_b32_e32 v53, v53, v207, vcc
	s_and_b64 vcc, vcc, s[26:27]
	v_cndmask_b32_e32 v52, v52, v207, vcc
	s_and_b64 vcc, vcc, s[22:23]
	v_cndmask_b32_e32 v51, v51, v207, vcc
	s_and_b64 vcc, vcc, s[18:19]
	v_cndmask_b32_e32 v50, v50, v207, vcc
	s_and_b64 vcc, vcc, s[14:15]
	v_cndmask_b32_e32 v49, v49, v207, vcc
	s_and_b64 vcc, vcc, s[10:11]
	v_cndmask_b32_e64 v63, v63, v207, s[72:73]
	v_cndmask_b32_e32 v48, v48, v207, vcc

; #define MFMA32(a, b, c) __builtin_amdgcn_mfma_f32_32x32x16_bf16((a), (b), (c), 0, 0, 0)
; #define SBAR() __builtin_amdgcn_sched_barrier(0)
; DI s16x4 trrd(const lds8* p) { typedef short v4i16_t __attribute__((ext_vector_type(4))); return __builtin_bit_cast(s16x4, __builtin_amdgcn_ds_read_tr16_b64_v4i16((LAS v4i16_t*)p)); }
; template <int VSTR, int NDVB> DI void pv64(f32x16 (&O)[NDVB], const lds8* vp, const bf16x8 (&P)[4]) {
;   bf16x8 f[2][NDVB];
; #pragma unroll
;   for (int d = 0; d < NDVB; ++d) { const s16x4 lo = trrd(vp + d * 64), hi = trrd(vp + 8 * VSTR + d * 64); f[0][d] = __builtin_shufflevector(lo, hi, 0, 1, 2, 3, 4, 5, 6, 7); }
; #pragma unroll
;   for (int kk = 0; kk < 4; ++kk) {
;     if (kk < 3) {
; #pragma unroll
;       for (int d = 0; d < NDVB; ++d) { const s16x4 lo = trrd(vp + (16 * (kk + 1)) * VSTR + d * 64), hi = trrd(vp + (16 * (kk + 1) + 8) * VSTR + d * 64);
;         f[(kk + 1) & 1][d] = __builtin_shufflevector(lo, hi, 0, 1, 2, 3, 4, 5, 6, 7); }
;     }
;     SBAR();
;     __builtin_amdgcn_s_setprio(1);
; #pragma unroll
;     for (int d = 0; d < NDVB; ++d) O[d] = MFMA32(f[kk & 1][d], P[kk], O[d]);
;     __builtin_amdgcn_s_setprio(0);
;     SBAR();
;   }
; }
.Lns_ma:
	s_setprio 0
	s_waitcnt lgkmcnt(6)
	v_mfma_f32_32x32x16_bf16 v[0:15], v[44:47], v[32:35], v[0:15]
	s_waitcnt lgkmcnt(4)
	v_mfma_f32_32x32x16_bf16 v[16:31], v[48:51], v[32:35], v[16:31]
	s_setprio 0
	ds_read_b64_tr_b16 v[32:33], v60 offset:13824
	ds_read_b64_tr_b16 v[34:35], v60 offset:14976
	ds_read_b64_tr_b16 v[46:47], v60 offset:15040
	ds_read_b64_tr_b16 v[44:45], v60 offset:13888
	s_setprio 0
	s_waitcnt lgkmcnt(6)
	v_mfma_f32_32x32x16_bf16 v[0:15], v[52:55], v[36:39], v[0:15]
	s_waitcnt lgkmcnt(4)
	v_mfma_f32_32x32x16_bf16 v[16:31], v[56:59], v[36:39], v[16:31]
	s_setprio 0
	ds_read_b64_tr_b16 v[48:49], v60 offset:16128
	ds_read_b64_tr_b16 v[50:51], v60 offset:17280
	ds_read_b64_tr_b16 v[146:147], v60 offset:17344
	ds_read_b64_tr_b16 v[144:145], v60 offset:16192
	s_setprio 0
	s_waitcnt lgkmcnt(6)
	v_mfma_f32_32x32x16_bf16 v[0:15], v[32:35], v[40:43], v[0:15]
	s_waitcnt lgkmcnt(4)
	v_mfma_f32_32x32x16_bf16 v[16:31], v[44:47], v[40:43], v[16:31]
	s_setprio 0
	s_setprio 0
	s_waitcnt lgkmcnt(2)
	v_mfma_f32_32x32x16_bf16 v[0:15], v[48:51], v[140:143], v[0:15]
	s_waitcnt lgkmcnt(0)
	v_mfma_f32_32x32x16_bf16 v[16:31], v[144:147], v[140:143], v[16:31]
	s_setprio 0
	v_readfirstlane_b32 vcc_lo, v200
	s_nop 1
	s_and_b32 vcc_lo, vcc_lo, 0x140
	s_bcnt1_i32_b32 vcc_lo, vcc_lo
	s_bitcmp1_b32 vcc_lo, 0
	s_cbranch_scc1 .Lns_ta
	s_barrier

; #define LAS __attribute__((address_space(3)))
; #define MFMA32(a, b, c) __builtin_amdgcn_mfma_f32_32x32x16_bf16((a), (b), (c), 0, 0, 0)
; #define SBAR() __builtin_amdgcn_sched_barrier(0)
; template <int KSTR> DI void qk64b(f32x16& s0, f32x16& s1, const lds8* kp, const bf16x8 (&q)[4], float bias) {
;   bf16x8 a[8];
; #pragma unroll
;   for (int ks = 0; ks < 4; ++ks) { a[2 * ks] = *(const LAS bf16x8*)(kp + ks * 32); a[2 * ks + 1] = *(const LAS bf16x8*)(kp + 32 * KSTR + ks * 32); }
; #pragma unroll
;   for (int i = 0; i < 16; ++i) { s0[i] = bias; s1[i] = bias; }
;   SBAR();
;   __builtin_amdgcn_s_setprio(1);
; #pragma unroll
;   for (int ks = 0; ks < 4; ++ks) { s0 = MFMA32(a[2 * ks], q[ks], s0); s1 = MFMA32(a[2 * ks + 1], q[ks], s1); }
;   __builtin_amdgcn_s_setprio(0);
;   SBAR();
; }
; template <int MODE, int SLOT> DI void ns_valu(volatile LAS int* jl, int t, int ntl, int qpos, int h, int blk, f32x16& s0, f32x16& s1, f32x16& du0, f32x16& du1, f32x16 (&O)[2], float& muse, float& l, bf16x8 (&P)[4], CmpCap& cap) {
;     ...
;       } else if (MODE == 1) {
;         if (j == blk) {
;           const int lim = qpos - 64 * j - 4 * h;
; #pragma unroll
;           for (int i = 0; i < 16; ++i) { const int ci = (i & 3) + 8 * (i >> 2); if (ci > lim) s0[i] = NEG; if (ci + 32 > lim) s1[i] = NEG; }
;         }
.LBB0_956:
	s_add_i32 s84, s6, 1
	s_cmp_lg_u32 s6, 2
	s_cselect_b32 s6, s84, 0
	v_mov_b32_e32 v140, s90
	ds_read_b32 v32, v140 offset:4
	s_mul_i32 s86, s6, 0x4800
	s_add_i32 s87, s86, 0
	v_add_u32_e32 v60, s87, v213
	s_waitcnt lgkmcnt(0)
	v_readfirstlane_b32 s84, v32
	s_nop 1
	v_lshrrev_b32_e32 v32, s84, v137
	v_and_b32_e32 v32, 1, v32
	v_cmp_eq_u32_e32 vcc, 1, v32
	ds_read_b128 v[32:35], v60 offset:4608
	ds_read_b128 v[36:39], v60
	ds_read_b128 v[40:43], v60 offset:32
	ds_read_b128 v[44:47], v60 offset:4640
	ds_read_b128 v[48:51], v60 offset:64
	ds_read_b128 v[52:55], v60 offset:4672
	ds_read_b128 v[56:59], v60 offset:96
	ds_read_b128 v[60:63], v60 offset:4704
	v_cndmask_b32_e64 v96, v207, -v138, vcc
	v_mov_b32_e32 v97, v96
	v_mov_b32_e32 v98, v96
	v_mov_b32_e32 v99, v96
	v_mov_b32_e32 v100, v96
	v_mov_b32_e32 v101, v96
	v_mov_b32_e32 v102, v96
	v_mov_b32_e32 v103, v96
	v_mov_b32_e32 v104, v96
	v_mov_b32_e32 v105, v96
	v_mov_b32_e32 v106, v96
	v_mov_b32_e32 v107, v96
	v_mov_b32_e32 v108, v96
	v_mov_b32_e32 v109, v96
	v_mov_b32_e32 v110, v96
	v_mov_b32_e32 v111, v96
	s_setprio 0
	s_waitcnt lgkmcnt(6)
	v_mfma_f32_32x32x16_bf16 v[112:127], v[36:39], v[160:163], v[96:111]
	v_mfma_f32_32x32x16_bf16 v[96:111], v[32:35], v[160:163], v[96:111]
	s_waitcnt lgkmcnt(5)
	v_mfma_f32_32x32x16_bf16 v[112:127], v[40:43], v[168:171], v[112:127]
	s_waitcnt lgkmcnt(4)
	v_mfma_f32_32x32x16_bf16 v[96:111], v[44:47], v[168:171], v[96:111]
	s_waitcnt lgkmcnt(3)
	v_mfma_f32_32x32x16_bf16 v[112:127], v[48:51], v[164:167], v[112:127]
	s_waitcnt lgkmcnt(2)
	v_mfma_f32_32x32x16_bf16 v[96:111], v[52:55], v[164:167], v[96:111]
	s_waitcnt lgkmcnt(1)
	v_mfma_f32_32x32x16_bf16 v[112:127], v[56:59], v[172:175], v[112:127]
	s_waitcnt lgkmcnt(0)
	v_mfma_f32_32x32x16_bf16 v[96:111], v[60:63], v[172:175], v[96:111]
	s_setprio 0
	s_cmp_lg_u32 s84, s77
	s_cbranch_scc1 .LBB0_960
	s_and_b64 vcc, s[70:71], s[66:67]
	s_nop 7
	v_cndmask_b32_e32 v109, v109, v207, vcc
	s_and_b64 vcc, vcc, s[62:63]
	v_cndmask_b32_e32 v108, v108, v207, vcc
	s_and_b64 vcc, vcc, s[58:59]
	v_cndmask_b32_e32 v107, v107, v207, vcc
	s_and_b64 vcc, vcc, s[54:55]
	v_cndmask_b32_e32 v106, v106, v207, vcc
	s_and_b64 vcc, vcc, s[50:51]
	v_cndmask_b32_e32 v105, v105, v207, vcc
	s_and_b64 vcc, vcc, s[46:47]
	v_cndmask_b32_e32 v104, v104, v207, vcc
	s_and_b64 vcc, vcc, s[42:43]
	v_cndmask_b32_e32 v103, v103, v207, vcc
	s_and_b64 vcc, vcc, s[38:39]
	v_cndmask_b32_e32 v102, v102, v207, vcc
	s_and_b64 vcc, vcc, s[34:35]
	v_cndmask_b32_e32 v101, v101, v207, vcc
	s_and_b64 vcc, vcc, s[28:29]
	v_cndmask_b32_e32 v100, v100, v207, vcc
	s_and_b64 vcc, vcc, s[24:25]
	v_cndmask_b32_e32 v99, v99, v207, vcc
	s_and_b64 vcc, vcc, s[20:21]
	v_cndmask_b32_e32 v98, v98, v207, vcc
	s_and_b64 vcc, vcc, s[16:17]
	v_cndmask_b32_e32 v97, v97, v207, vcc
	s_and_b64 vcc, vcc, s[12:13]
	v_cndmask_b32_e64 v110, v110, v207, s[70:71]
	v_cndmask_b32_e32 v96, v96, v207, vcc
	s_and_saveexec_b64 s[84:85], s[74:75]
	s_mov_b32 s94, 0xf149f2ca
	v_mov_b32_e32 v111, s94
	s_or_b64 exec, exec, s[84:85]
	s_and_b64 vcc, s[72:73], s[68:69]
	v_cndmask_b32_e32 v126, v126, v207, vcc
	s_and_b64 vcc, vcc, s[64:65]
	v_cndmask_b32_e32 v125, v125, v207, vcc
	s_and_b64 vcc, vcc, s[60:61]
	v_cndmask_b32_e32 v124, v124, v207, vcc
	s_and_b64 vcc, vcc, s[56:57]
	v_cndmask_b32_e32 v123, v123, v207, vcc
	s_and_b64 vcc, vcc, s[52:53]
	v_cndmask_b32_e32 v122, v122, v207, vcc
	s_and_b64 vcc, vcc, s[48:49]
	v_cndmask_b32_e32 v121, v121, v207, vcc
	s_and_b64 vcc, vcc, s[44:45]
	v_cndmask_b32_e32 v120, v120, v207, vcc
	s_and_b64 vcc, vcc, s[40:41]
	v_cndmask_b32_e32 v119, v119, v207, vcc
	s_and_b64 vcc, vcc, s[36:37]
	v_cndmask_b32_e32 v118, v118, v207, vcc
	s_and_b64 vcc, vcc, s[30:31]
	v_cndmask_b32_e32 v117, v117, v207, vcc
	s_and_b64 vcc, vcc, s[26:27]
	v_cndmask_b32_e32 v116, v116, v207, vcc
	s_and_b64 vcc, vcc, s[22:23]
	v_cndmask_b32_e32 v115, v115, v207, vcc
	s_and_b64 vcc, vcc, s[18:19]
	v_cndmask_b32_e32 v114, v114, v207, vcc
	s_and_b64 vcc, vcc, s[14:15]
	v_cndmask_b32_e32 v113, v113, v207, vcc
	s_and_b64 vcc, vcc, s[10:11]
	v_cndmask_b32_e64 v127, v127, v207, s[72:73]
	v_cndmask_b32_e32 v112, v112, v207, vcc

; #define MFMA32(a, b, c) __builtin_amdgcn_mfma_f32_32x32x16_bf16((a), (b), (c), 0, 0, 0)
; #define SBAR() __builtin_amdgcn_sched_barrier(0)
; DI s16x4 trrd(const lds8* p) { typedef short v4i16_t __attribute__((ext_vector_type(4))); return __builtin_bit_cast(s16x4, __builtin_amdgcn_ds_read_tr16_b64_v4i16((LAS v4i16_t*)p)); }
; template <int VSTR, int NDVB> DI void pv64(f32x16 (&O)[NDVB], const lds8* vp, const bf16x8 (&P)[4]) {
;   bf16x8 f[2][NDVB];
; #pragma unroll
;   for (int d = 0; d < NDVB; ++d) { const s16x4 lo = trrd(vp + d * 64), hi = trrd(vp + 8 * VSTR + d * 64); f[0][d] = __builtin_shufflevector(lo, hi, 0, 1, 2, 3, 4, 5, 6, 7); }
; #pragma unroll
;   for (int kk = 0; kk < 4; ++kk) {
;     if (kk < 3) {
; #pragma unroll
;       for (int d = 0; d < NDVB; ++d) { const s16x4 lo = trrd(vp + (16 * (kk + 1)) * VSTR + d * 64), hi = trrd(vp + (16 * (kk + 1) + 8) * VSTR + d * 64);
;         f[(kk + 1) & 1][d] = __builtin_shufflevector(lo, hi, 0, 1, 2, 3, 4, 5, 6, 7); }
;     }
;     SBAR();
;     __builtin_amdgcn_s_setprio(1);
; #pragma unroll
;     for (int d = 0; d < NDVB; ++d) O[d] = MFMA32(f[kk & 1][d], P[kk], O[d]);
;     __builtin_amdgcn_s_setprio(0);
;     SBAR();
;   }
; }
.Lns_mb:
	s_setprio 0
	s_waitcnt lgkmcnt(6)
	v_mfma_f32_32x32x16_bf16 v[0:15], v[154:157], v[142:145], v[0:15]
	s_waitcnt lgkmcnt(4)
	v_mfma_f32_32x32x16_bf16 v[16:31], v[176:179], v[142:145], v[16:31]
	s_setprio 0
	ds_read_b64_tr_b16 v[142:143], v141 offset:13824
	ds_read_b64_tr_b16 v[144:145], v141 offset:14976
	ds_read_b64_tr_b16 v[156:157], v141 offset:15040
	ds_read_b64_tr_b16 v[154:155], v141 offset:13888
	s_setprio 0
	s_waitcnt lgkmcnt(6)
	v_mfma_f32_32x32x16_bf16 v[0:15], v[180:183], v[146:149], v[0:15]
	s_waitcnt lgkmcnt(4)
	v_mfma_f32_32x32x16_bf16 v[16:31], v[220:223], v[146:149], v[16:31]
	s_setprio 0
	ds_read_b64_tr_b16 v[146:147], v141 offset:16128
	ds_read_b64_tr_b16 v[148:149], v141 offset:17280
	ds_read_b64_tr_b16 v[178:179], v141 offset:17344
	ds_read_b64_tr_b16 v[176:177], v141 offset:16192
	s_setprio 0
	s_waitcnt lgkmcnt(6)
	v_mfma_f32_32x32x16_bf16 v[0:15], v[142:145], v[150:153], v[0:15]
	s_waitcnt lgkmcnt(4)
	v_mfma_f32_32x32x16_bf16 v[16:31], v[154:157], v[150:153], v[16:31]
	s_setprio 0
	s_setprio 0
	s_waitcnt lgkmcnt(2)
	v_mfma_f32_32x32x16_bf16 v[0:15], v[146:149], v[224:227], v[0:15]
	s_waitcnt lgkmcnt(0)
	v_mfma_f32_32x32x16_bf16 v[16:31], v[176:179], v[224:227], v[16:31]
	s_setprio 0
	v_readfirstlane_b32 vcc_lo, v200
	s_nop 1
	s_and_b32 vcc_lo, vcc_lo, 0x140
	s_bcnt1_i32_b32 vcc_lo, vcc_lo
	s_bitcmp1_b32 vcc_lo, 0
	s_cbranch_scc1 .Lns_tb
	s_barrier

; #define LAS __attribute__((address_space(3)))
; #define MFMA32(a, b, c) __builtin_amdgcn_mfma_f32_32x32x16_bf16((a), (b), (c), 0, 0, 0)
; #define SBAR() __builtin_amdgcn_sched_barrier(0)
; template <int KSTR> DI void qk64b(f32x16& s0, f32x16& s1, const lds8* kp, const bf16x8 (&q)[4], float bias) {
;   bf16x8 a[8];
; #pragma unroll
;   for (int ks = 0; ks < 4; ++ks) { a[2 * ks] = *(const LAS bf16x8*)(kp + ks * 32); a[2 * ks + 1] = *(const LAS bf16x8*)(kp + 32 * KSTR + ks * 32); }
; #pragma unroll
;   for (int i = 0; i < 16; ++i) { s0[i] = bias; s1[i] = bias; }
;   SBAR();
;   __builtin_amdgcn_s_setprio(1);
; #pragma unroll
;   for (int ks = 0; ks < 4; ++ks) { s0 = MFMA32(a[2 * ks], q[ks], s0); s1 = MFMA32(a[2 * ks + 1], q[ks], s1); }
;   __builtin_amdgcn_s_setprio(0);
;   SBAR();
; }
; template <int MODE, int SLOT> DI void ns_valu(volatile LAS int* jl, int t, int ntl, int qpos, int h, int blk, f32x16& s0, f32x16& s1, f32x16& du0, f32x16& du1, f32x16 (&O)[2], float& muse, float& l, bf16x8 (&P)[4], CmpCap& cap) {
;     ...
;       } else {
;         if (j == blk || j + 8 == blk) {
;           const int lim = qpos - 64 * j - 4 * h, lo = lim - 512;
; #pragma unroll
;           for (int i = 0; i < 16; ++i) { const int ci = (i & 3) + 8 * (i >> 2); if (ci > lim || ci <= lo) s0[i] = NEG; if (ci + 32 > lim || ci + 32 <= lo) s1[i] = NEG; }
;         }
.LBB0_983:
	s_mul_i32 s48, s6, 0x4800
	s_add_i32 s49, s48, 0
	v_add_u32_e32 v97, s49, v213
	ds_read_b128 v[130:133], v97
	ds_read_b128 v[134:137], v97 offset:32
	ds_read_b128 v[138:141], v97 offset:4608
	ds_read_b128 v[142:145], v97 offset:4640
	ds_read_b128 v[146:149], v97 offset:64
	ds_read_b128 v[150:153], v97 offset:96
	ds_read_b128 v[154:157], v97 offset:4672
	ds_read_b128 v[222:225], v97 offset:4704
	v_xor_b32_e32 v96, 0x80000000, v221
	v_mov_b32_e32 v97, v96
	v_mov_b32_e32 v98, v96
	v_mov_b32_e32 v99, v96
	v_mov_b32_e32 v100, v96
	v_mov_b32_e32 v101, v96
	v_mov_b32_e32 v102, v96
	v_mov_b32_e32 v103, v96
	v_mov_b32_e32 v104, v96
	v_mov_b32_e32 v105, v96
	v_mov_b32_e32 v106, v96
	v_mov_b32_e32 v107, v96
	v_mov_b32_e32 v108, v96
	v_mov_b32_e32 v109, v96
	v_mov_b32_e32 v110, v96
	v_mov_b32_e32 v111, v96
	s_setprio 0
	s_waitcnt lgkmcnt(7)
	v_mfma_f32_32x32x16_bf16 v[112:127], v[130:133], v[160:163], v[96:111]
	s_waitcnt lgkmcnt(5)
	v_mfma_f32_32x32x16_bf16 v[96:111], v[138:141], v[160:163], v[96:111]
	v_mfma_f32_32x32x16_bf16 v[112:127], v[134:137], v[168:171], v[112:127]
	s_waitcnt lgkmcnt(4)
	v_mfma_f32_32x32x16_bf16 v[96:111], v[142:145], v[168:171], v[96:111]
	s_waitcnt lgkmcnt(3)
	v_mfma_f32_32x32x16_bf16 v[112:127], v[146:149], v[164:167], v[112:127]
	s_waitcnt lgkmcnt(1)
	v_mfma_f32_32x32x16_bf16 v[96:111], v[154:157], v[164:167], v[96:111]
	v_mfma_f32_32x32x16_bf16 v[112:127], v[150:153], v[172:175], v[112:127]
	s_waitcnt lgkmcnt(0)
	v_mfma_f32_32x32x16_bf16 v[96:111], v[222:225], v[172:175], v[96:111]
	s_setprio 0
	v_mov_b32_e32 v129, s0
	ds_read_b32 v129, v129
	s_waitcnt lgkmcnt(0)
	v_readfirstlane_b32 s8, v129
	s_cmp_eq_u32 s8, s77
	s_cselect_b64 s[10:11], -1, 0
	s_add_i32 s9, s8, 8
	s_cmp_eq_u32 s9, s77
	s_cselect_b64 s[12:13], -1, 0
	s_or_b64 s[10:11], s[10:11], s[12:13]
	s_andn2_b64 vcc, exec, s[10:11]
	s_cbranch_vccnz .LBB0_987
	v_lshl_or_b32 v129, s8, 6, v214
	v_sub_u32_e32 v129, v211, v129
	v_subrev_u32_e32 v130, 32, v129
	v_cmp_gt_u32_e64 s[8:9], s33, v130
	v_add_u32_e32 v130, -1, v129
	v_cmp_gt_u32_e32 vcc, s33, v129
	v_cndmask_b32_e64 v96, v207, v96, s[8:9]
	v_cmp_gt_u32_e64 s[8:9], s33, v130
	v_subrev_u32_e32 v130, 33, v129
	v_cmp_gt_u32_e64 s[10:11], s33, v130
	v_add_u32_e32 v130, -2, v129
	s_nop 0
	v_cndmask_b32_e64 v97, v207, v97, s[10:11]
	v_cmp_gt_u32_e64 s[10:11], s33, v130
	v_subrev_u32_e32 v130, 34, v129
	v_cmp_gt_u32_e64 s[12:13], s33, v130
	v_add_u32_e32 v130, -3, v129
	s_nop 0
	v_cndmask_b32_e64 v98, v207, v98, s[12:13]
	v_cmp_gt_u32_e64 s[12:13], s33, v130
	v_subrev_u32_e32 v130, 35, v129
	v_cmp_gt_u32_e64 s[14:15], s33, v130
	v_add_u32_e32 v130, -8, v129
	s_nop 0
	v_cndmask_b32_e64 v99, v207, v99, s[14:15]
	v_cmp_gt_u32_e64 s[14:15], s33, v130
	v_subrev_u32_e32 v130, 40, v129
	v_cmp_gt_u32_e64 s[16:17], s33, v130
	v_add_u32_e32 v130, -9, v129
	s_nop 0
	v_cndmask_b32_e64 v100, v207, v100, s[16:17]
	v_cmp_gt_u32_e64 s[16:17], s33, v130
	v_subrev_u32_e32 v130, 41, v129
	v_cmp_gt_u32_e64 s[18:19], s33, v130
	v_add_u32_e32 v130, -10, v129
	s_nop 0
	v_cndmask_b32_e64 v101, v207, v101, s[18:19]
	v_cmp_gt_u32_e64 s[18:19], s33, v130
	v_subrev_u32_e32 v130, 42, v129
	v_cmp_gt_u32_e64 s[20:21], s33, v130
	v_add_u32_e32 v130, -11, v129
	s_nop 0
	v_cndmask_b32_e64 v102, v207, v102, s[20:21]
	v_cmp_gt_u32_e64 s[20:21], s33, v130
	v_subrev_u32_e32 v130, 43, v129
	v_cmp_gt_u32_e64 s[22:23], s33, v130
	v_add_u32_e32 v130, -16, v129
	s_nop 0
	v_cndmask_b32_e64 v103, v207, v103, s[22:23]
	v_cmp_gt_u32_e64 s[22:23], s33, v130
	v_subrev_u32_e32 v130, 48, v129
	v_cmp_gt_u32_e64 s[24:25], s33, v130
	v_subrev_u32_e32 v130, 17, v129
	s_nop 0
	v_cndmask_b32_e64 v104, v207, v104, s[24:25]
	v_cmp_gt_u32_e64 s[24:25], s33, v130
	v_subrev_u32_e32 v130, 49, v129
	v_cmp_gt_u32_e64 s[26:27], s33, v130
	v_subrev_u32_e32 v130, 18, v129
	s_nop 0
	v_cndmask_b32_e64 v105, v207, v105, s[26:27]
	v_cmp_gt_u32_e64 s[26:27], s33, v130
	v_subrev_u32_e32 v130, 50, v129
	v_cmp_gt_u32_e64 s[28:29], s33, v130
	v_subrev_u32_e32 v130, 19, v129
	s_nop 0
	v_cndmask_b32_e64 v106, v207, v106, s[28:29]
	v_cmp_gt_u32_e64 s[28:29], s33, v130
	v_subrev_u32_e32 v130, 51, v129
	v_cmp_gt_u32_e64 s[30:31], s33, v130
	v_subrev_u32_e32 v130, 24, v129
	s_nop 0
	v_cndmask_b32_e64 v107, v207, v107, s[30:31]
	v_cmp_gt_u32_e64 s[30:31], s33, v130
	v_subrev_u32_e32 v130, 56, v129
	v_cmp_gt_u32_e64 s[34:35], s33, v130
	v_subrev_u32_e32 v130, 25, v129
	s_nop 0
	v_cndmask_b32_e64 v108, v207, v108, s[34:35]
	v_cmp_gt_u32_e64 s[34:35], s33, v130
	v_subrev_u32_e32 v130, 57, v129
	v_cmp_gt_u32_e64 s[36:37], s33, v130
	v_subrev_u32_e32 v130, 26, v129
	s_nop 0
	v_cndmask_b32_e64 v109, v207, v109, s[36:37]
	v_cmp_gt_u32_e64 s[36:37], s33, v130
	v_subrev_u32_e32 v130, 58, v129
	v_cmp_gt_u32_e64 s[38:39], s33, v130
	v_subrev_u32_e32 v130, 27, v129
	v_subrev_u32_e32 v129, 59, v129
	v_cndmask_b32_e64 v110, v207, v110, s[38:39]
	v_cmp_gt_u32_e64 s[38:39], s33, v130
	v_cmp_lt_u32_e64 s[40:41], s95, v129
	s_and_saveexec_b64 s[44:45], s[40:41]
	s_mov_b32 s1, 0xf149f2ca
	v_mov_b32_e32 v111, s1
	s_or_b64 exec, exec, s[44:45]
	v_cndmask_b32_e32 v112, v207, v112, vcc
	v_cndmask_b32_e64 v113, v207, v113, s[8:9]
	v_cndmask_b32_e64 v114, v207, v114, s[10:11]
	v_cndmask_b32_e64 v115, v207, v115, s[12:13]
	v_cndmask_b32_e64 v116, v207, v116, s[14:15]
	v_cndmask_b32_e64 v117, v207, v117, s[16:17]
	v_cndmask_b32_e64 v118, v207, v118, s[18:19]
	v_cndmask_b32_e64 v119, v207, v119, s[20:21]
	v_cndmask_b32_e64 v120, v207, v120, s[22:23]
	v_cndmask_b32_e64 v121, v207, v121, s[24:25]
	v_cndmask_b32_e64 v122, v207, v122, s[26:27]
	v_cndmask_b32_e64 v123, v207, v123, s[28:29]
	v_cndmask_b32_e64 v124, v207, v124, s[30:31]
	v_cndmask_b32_e64 v125, v207, v125, s[34:35]
	v_cndmask_b32_e64 v126, v207, v126, s[36:37]
	v_cndmask_b32_e64 v127, v207, v127, s[38:39]

; #define MFMA32(a, b, c) __builtin_amdgcn_mfma_f32_32x32x16_bf16((a), (b), (c), 0, 0, 0)
; #define SBAR() __builtin_amdgcn_sched_barrier(0)
; DI s16x4 trrd(const lds8* p) { typedef short v4i16_t __attribute__((ext_vector_type(4))); return __builtin_bit_cast(s16x4, __builtin_amdgcn_ds_read_tr16_b64_v4i16((LAS v4i16_t*)p)); }
; template <int VSTR, int NDVB> DI void pv64(f32x16 (&O)[NDVB], const lds8* vp, const bf16x8 (&P)[4]) {
;   bf16x8 f[2][NDVB];
; #pragma unroll
;   for (int d = 0; d < NDVB; ++d) { const s16x4 lo = trrd(vp + d * 64), hi = trrd(vp + 8 * VSTR + d * 64); f[0][d] = __builtin_shufflevector(lo, hi, 0, 1, 2, 3, 4, 5, 6, 7); }
; #pragma unroll
;   for (int kk = 0; kk < 4; ++kk) {
;     if (kk < 3) {
; #pragma unroll
;       for (int d = 0; d < NDVB; ++d) { const s16x4 lo = trrd(vp + (16 * (kk + 1)) * VSTR + d * 64), hi = trrd(vp + (16 * (kk + 1) + 8) * VSTR + d * 64);
;         f[(kk + 1) & 1][d] = __builtin_shufflevector(lo, hi, 0, 1, 2, 3, 4, 5, 6, 7); }
;     }
;     SBAR();
;     __builtin_amdgcn_s_setprio(1);
; #pragma unroll
;     for (int d = 0; d < NDVB; ++d) O[d] = MFMA32(f[kk & 1][d], P[kk], O[d]);
;     __builtin_amdgcn_s_setprio(0);
;     SBAR();
;   }
; }
.Lns_mc:
	s_setprio 0
	s_waitcnt lgkmcnt(6)
	v_mfma_f32_32x32x16_bf16 v[32:47], v[108:111], v[96:99], v[32:47]
	s_waitcnt lgkmcnt(4)
	v_mfma_f32_32x32x16_bf16 v[48:63], v[112:115], v[96:99], v[48:63]
	s_setprio 0
	ds_read_b64_tr_b16 v[96:97], v124 offset:13824
	ds_read_b64_tr_b16 v[98:99], v124 offset:14976
	ds_read_b64_tr_b16 v[110:111], v124 offset:15040
	ds_read_b64_tr_b16 v[108:109], v124 offset:13888
	s_setprio 0
	s_waitcnt lgkmcnt(6)
	v_mfma_f32_32x32x16_bf16 v[32:47], v[116:119], v[100:103], v[32:47]
	s_waitcnt lgkmcnt(4)
	v_mfma_f32_32x32x16_bf16 v[48:63], v[120:123], v[100:103], v[48:63]
	s_setprio 0
	ds_read_b64_tr_b16 v[112:113], v124 offset:16128
	ds_read_b64_tr_b16 v[114:115], v124 offset:17280
	ds_read_b64_tr_b16 v[230:231], v124 offset:17344
	ds_read_b64_tr_b16 v[228:229], v124 offset:16192
	s_setprio 0
	s_waitcnt lgkmcnt(6)
	v_mfma_f32_32x32x16_bf16 v[32:47], v[96:99], v[104:107], v[32:47]
	s_waitcnt lgkmcnt(4)
	v_mfma_f32_32x32x16_bf16 v[48:63], v[108:111], v[104:107], v[48:63]
	s_setprio 0
	s_setprio 0
	s_waitcnt lgkmcnt(2)
	v_mfma_f32_32x32x16_bf16 v[32:47], v[112:115], v[224:227], v[32:47]
	s_waitcnt lgkmcnt(0)
	v_mfma_f32_32x32x16_bf16 v[48:63], v[228:231], v[224:227], v[48:63]
	s_setprio 0
	v_readfirstlane_b32 vcc_lo, v200
	s_nop 1
	s_and_b32 vcc_lo, vcc_lo, 0x140
	s_bcnt1_i32_b32 vcc_lo, vcc_lo
	s_bitcmp1_b32 vcc_lo, 0
	s_cbranch_scc1 .Lns_tc
	s_barrier

; #define LAS __attribute__((address_space(3)))
; #define MFMA32(a, b, c) __builtin_amdgcn_mfma_f32_32x32x16_bf16((a), (b), (c), 0, 0, 0)
; #define SBAR() __builtin_amdgcn_sched_barrier(0)
; template <int KSTR> DI void qk64b(f32x16& s0, f32x16& s1, const lds8* kp, const bf16x8 (&q)[4], float bias) {
;   bf16x8 a[8];
; #pragma unroll
;   for (int ks = 0; ks < 4; ++ks) { a[2 * ks] = *(const LAS bf16x8*)(kp + ks * 32); a[2 * ks + 1] = *(const LAS bf16x8*)(kp + 32 * KSTR + ks * 32); }
; #pragma unroll
;   for (int i = 0; i < 16; ++i) { s0[i] = bias; s1[i] = bias; }
;   SBAR();
;   __builtin_amdgcn_s_setprio(1);
; #pragma unroll
;   for (int ks = 0; ks < 4; ++ks) { s0 = MFMA32(a[2 * ks], q[ks], s0); s1 = MFMA32(a[2 * ks + 1], q[ks], s1); }
;   __builtin_amdgcn_s_setprio(0);
;   SBAR();
; }
; template <int MODE, int SLOT> DI void ns_valu(volatile LAS int* jl, int t, int ntl, int qpos, int h, int blk, f32x16& s0, f32x16& s1, f32x16& du0, f32x16& du1, f32x16 (&O)[2], float& muse, float& l, bf16x8 (&P)[4], CmpCap& cap) {
;     ...
;       } else {
;         if (j == blk || j + 8 == blk) {
;           const int lim = qpos - 64 * j - 4 * h, lo = lim - 512;
; #pragma unroll
;           for (int i = 0; i < 16; ++i) { const int ci = (i & 3) + 8 * (i >> 2); if (ci > lim || ci <= lo) s0[i] = NEG; if (ci + 32 > lim || ci + 32 <= lo) s1[i] = NEG; }
;         }
.LBB0_999:
	s_add_i32 s8, s6, 1
	s_cmp_lg_u32 s6, 2
	s_cselect_b32 s6, s8, 0
	s_mul_i32 s48, s6, 0x4800
	s_add_i32 s49, s48, 0
	v_add_u32_e32 v124, s49, v213
	ds_read_b128 v[96:99], v124
	ds_read_b128 v[100:103], v124 offset:32
	ds_read_b128 v[104:107], v124 offset:4608
	ds_read_b128 v[108:111], v124 offset:4640
	ds_read_b128 v[112:115], v124 offset:64
	ds_read_b128 v[116:119], v124 offset:96
	ds_read_b128 v[120:123], v124 offset:4672
	ds_read_b128 v[124:127], v124 offset:4704
	v_xor_b32_e32 v128, 0x80000000, v221
	v_mov_b32_e32 v129, v128
	v_mov_b32_e32 v130, v128
	v_mov_b32_e32 v131, v128
	v_mov_b32_e32 v132, v128
	v_mov_b32_e32 v133, v128
	v_mov_b32_e32 v134, v128
	v_mov_b32_e32 v135, v128
	v_mov_b32_e32 v136, v128
	v_mov_b32_e32 v137, v128
	v_mov_b32_e32 v138, v128
	v_mov_b32_e32 v139, v128
	v_mov_b32_e32 v140, v128
	v_mov_b32_e32 v141, v128
	v_mov_b32_e32 v142, v128
	v_mov_b32_e32 v143, v128
	s_setprio 0
	s_waitcnt lgkmcnt(7)
	v_mfma_f32_32x32x16_bf16 v[144:159], v[96:99], v[160:163], v[128:143]
	s_waitcnt lgkmcnt(5)
	v_mfma_f32_32x32x16_bf16 v[128:143], v[104:107], v[160:163], v[128:143]
	v_mfma_f32_32x32x16_bf16 v[144:159], v[100:103], v[168:171], v[144:159]
	s_waitcnt lgkmcnt(4)
	v_mfma_f32_32x32x16_bf16 v[128:143], v[108:111], v[168:171], v[128:143]
	s_waitcnt lgkmcnt(3)
	v_mfma_f32_32x32x16_bf16 v[144:159], v[112:115], v[164:167], v[144:159]
	s_waitcnt lgkmcnt(1)
	v_mfma_f32_32x32x16_bf16 v[128:143], v[120:123], v[164:167], v[128:143]
	v_mfma_f32_32x32x16_bf16 v[144:159], v[116:119], v[172:175], v[144:159]
	s_waitcnt lgkmcnt(0)
	v_mfma_f32_32x32x16_bf16 v[128:143], v[124:127], v[172:175], v[128:143]
	s_setprio 0
	v_mov_b32_e32 v96, s0
	ds_read_b32 v96, v96 offset:4
	s_waitcnt lgkmcnt(0)
	v_readfirstlane_b32 s8, v96
	s_cmp_eq_u32 s8, s77
	s_cselect_b64 s[10:11], -1, 0
	s_add_i32 s9, s8, 8
	s_cmp_eq_u32 s9, s77
	s_cselect_b64 s[12:13], -1, 0
	s_or_b64 s[10:11], s[10:11], s[12:13]
	s_andn2_b64 vcc, exec, s[10:11]
	s_cbranch_vccnz .LBB0_1003
	v_lshl_or_b32 v96, s8, 6, v214
	v_sub_u32_e32 v96, v211, v96
	v_subrev_u32_e32 v97, 32, v96
	v_cmp_gt_u32_e64 s[8:9], s33, v97
	v_add_u32_e32 v97, -1, v96
	v_cmp_gt_u32_e32 vcc, s33, v96
	v_cndmask_b32_e64 v128, v207, v128, s[8:9]
	v_cmp_gt_u32_e64 s[8:9], s33, v97
	v_subrev_u32_e32 v97, 33, v96
	v_cmp_gt_u32_e64 s[10:11], s33, v97
	v_add_u32_e32 v97, -2, v96
	s_nop 0
	v_cndmask_b32_e64 v129, v207, v129, s[10:11]
	v_cmp_gt_u32_e64 s[10:11], s33, v97
	v_subrev_u32_e32 v97, 34, v96
	v_cmp_gt_u32_e64 s[12:13], s33, v97
	v_add_u32_e32 v97, -3, v96
	s_nop 0
	v_cndmask_b32_e64 v130, v207, v130, s[12:13]
	v_cmp_gt_u32_e64 s[12:13], s33, v97
	v_subrev_u32_e32 v97, 35, v96
	v_cmp_gt_u32_e64 s[14:15], s33, v97
	v_add_u32_e32 v97, -8, v96
	s_nop 0
	v_cndmask_b32_e64 v131, v207, v131, s[14:15]
	v_cmp_gt_u32_e64 s[14:15], s33, v97
	v_subrev_u32_e32 v97, 40, v96
	v_cmp_gt_u32_e64 s[16:17], s33, v97
	v_add_u32_e32 v97, -9, v96
	s_nop 0
	v_cndmask_b32_e64 v132, v207, v132, s[16:17]
	v_cmp_gt_u32_e64 s[16:17], s33, v97
	v_subrev_u32_e32 v97, 41, v96
	v_cmp_gt_u32_e64 s[18:19], s33, v97
	v_add_u32_e32 v97, -10, v96
	s_nop 0
	v_cndmask_b32_e64 v133, v207, v133, s[18:19]
	v_cmp_gt_u32_e64 s[18:19], s33, v97
	v_subrev_u32_e32 v97, 42, v96
	v_cmp_gt_u32_e64 s[20:21], s33, v97
	v_add_u32_e32 v97, -11, v96
	s_nop 0
	v_cndmask_b32_e64 v134, v207, v134, s[20:21]
	v_cmp_gt_u32_e64 s[20:21], s33, v97
	v_subrev_u32_e32 v97, 43, v96
	v_cmp_gt_u32_e64 s[22:23], s33, v97
	v_add_u32_e32 v97, -16, v96
	s_nop 0
	v_cndmask_b32_e64 v135, v207, v135, s[22:23]
	v_cmp_gt_u32_e64 s[22:23], s33, v97
	v_subrev_u32_e32 v97, 48, v96
	v_cmp_gt_u32_e64 s[24:25], s33, v97
	v_subrev_u32_e32 v97, 17, v96
	s_nop 0
	v_cndmask_b32_e64 v136, v207, v136, s[24:25]
	v_cmp_gt_u32_e64 s[24:25], s33, v97
	v_subrev_u32_e32 v97, 49, v96
	v_cmp_gt_u32_e64 s[26:27], s33, v97
	v_subrev_u32_e32 v97, 18, v96
	s_nop 0
	v_cndmask_b32_e64 v137, v207, v137, s[26:27]
	v_cmp_gt_u32_e64 s[26:27], s33, v97
	v_subrev_u32_e32 v97, 50, v96
	v_cmp_gt_u32_e64 s[28:29], s33, v97
	v_subrev_u32_e32 v97, 19, v96
	s_nop 0
	v_cndmask_b32_e64 v138, v207, v138, s[28:29]
	v_cmp_gt_u32_e64 s[28:29], s33, v97
	v_subrev_u32_e32 v97, 51, v96
	v_cmp_gt_u32_e64 s[30:31], s33, v97
	v_subrev_u32_e32 v97, 24, v96
	s_nop 0
	v_cndmask_b32_e64 v139, v207, v139, s[30:31]
	v_cmp_gt_u32_e64 s[30:31], s33, v97
	v_subrev_u32_e32 v97, 56, v96
	v_cmp_gt_u32_e64 s[34:35], s33, v97
	v_subrev_u32_e32 v97, 25, v96
	s_nop 0
	v_cndmask_b32_e64 v140, v207, v140, s[34:35]
	v_cmp_gt_u32_e64 s[34:35], s33, v97
	v_subrev_u32_e32 v97, 57, v96
	v_cmp_gt_u32_e64 s[36:37], s33, v97
	v_subrev_u32_e32 v97, 26, v96
	s_nop 0
	v_cndmask_b32_e64 v141, v207, v141, s[36:37]
	v_cmp_gt_u32_e64 s[36:37], s33, v97
	v_subrev_u32_e32 v97, 58, v96
	v_cmp_gt_u32_e64 s[38:39], s33, v97
	v_subrev_u32_e32 v97, 27, v96
	v_subrev_u32_e32 v96, 59, v96
	v_cndmask_b32_e64 v142, v207, v142, s[38:39]
	v_cmp_gt_u32_e64 s[38:39], s33, v97
	v_cmp_lt_u32_e64 s[40:41], s95, v96
	s_and_saveexec_b64 s[44:45], s[40:41]
	s_mov_b32 s1, 0xf149f2ca
	v_mov_b32_e32 v143, s1
	s_or_b64 exec, exec, s[44:45]
	v_cndmask_b32_e32 v144, v207, v144, vcc
	v_cndmask_b32_e64 v145, v207, v145, s[8:9]
	v_cndmask_b32_e64 v146, v207, v146, s[10:11]
	v_cndmask_b32_e64 v147, v207, v147, s[12:13]
	v_cndmask_b32_e64 v148, v207, v148, s[14:15]
	v_cndmask_b32_e64 v149, v207, v149, s[16:17]
	v_cndmask_b32_e64 v150, v207, v150, s[18:19]
	v_cndmask_b32_e64 v151, v207, v151, s[20:21]
	v_cndmask_b32_e64 v152, v207, v152, s[22:23]
	v_cndmask_b32_e64 v153, v207, v153, s[24:25]
	v_cndmask_b32_e64 v154, v207, v154, s[26:27]
	v_cndmask_b32_e64 v155, v207, v155, s[28:29]
	v_cndmask_b32_e64 v156, v207, v156, s[30:31]
	v_cndmask_b32_e64 v157, v207, v157, s[34:35]
	v_cndmask_b32_e64 v158, v207, v158, s[36:37]
	v_cndmask_b32_e64 v159, v207, v159, s[38:39]

; #define MFMA32(a, b, c) __builtin_amdgcn_mfma_f32_32x32x16_bf16((a), (b), (c), 0, 0, 0)
; #define SBAR() __builtin_amdgcn_sched_barrier(0)
; DI s16x4 trrd(const lds8* p) { typedef short v4i16_t __attribute__((ext_vector_type(4))); return __builtin_bit_cast(s16x4, __builtin_amdgcn_ds_read_tr16_b64_v4i16((LAS v4i16_t*)p)); }
; template <int VSTR, int NDVB> DI void pv64(f32x16 (&O)[NDVB], const lds8* vp, const bf16x8 (&P)[4]) {
;   bf16x8 f[2][NDVB];
; #pragma unroll
;   for (int d = 0; d < NDVB; ++d) { const s16x4 lo = trrd(vp + d * 64), hi = trrd(vp + 8 * VSTR + d * 64); f[0][d] = __builtin_shufflevector(lo, hi, 0, 1, 2, 3, 4, 5, 6, 7); }
; #pragma unroll
;   for (int kk = 0; kk < 4; ++kk) {
;     if (kk < 3) {
; #pragma unroll
;       for (int d = 0; d < NDVB; ++d) { const s16x4 lo = trrd(vp + (16 * (kk + 1)) * VSTR + d * 64), hi = trrd(vp + (16 * (kk + 1) + 8) * VSTR + d * 64);
;         f[(kk + 1) & 1][d] = __builtin_shufflevector(lo, hi, 0, 1, 2, 3, 4, 5, 6, 7); }
;     }
;     SBAR();
;     __builtin_amdgcn_s_setprio(1);
; #pragma unroll
;     for (int d = 0; d < NDVB; ++d) O[d] = MFMA32(f[kk & 1][d], P[kk], O[d]);
;     __builtin_amdgcn_s_setprio(0);
;     SBAR();
;   }
; }
.Lns_md:
	s_setprio 0
	s_waitcnt lgkmcnt(6)
	v_mfma_f32_32x32x16_bf16 v[32:47], v[236:239], v[224:227], v[32:47]
	s_waitcnt lgkmcnt(4)
	v_mfma_f32_32x32x16_bf16 v[48:63], v[240:243], v[224:227], v[48:63]
	s_setprio 0
	ds_read_b64_tr_b16 v[224:225], v206 offset:13824
	ds_read_b64_tr_b16 v[226:227], v206 offset:14976
	ds_read_b64_tr_b16 v[238:239], v206 offset:15040
	ds_read_b64_tr_b16 v[236:237], v206 offset:13888
	s_setprio 0
	s_waitcnt lgkmcnt(6)
	v_mfma_f32_32x32x16_bf16 v[32:47], v[244:247], v[228:231], v[32:47]
	s_waitcnt lgkmcnt(4)
	v_mfma_f32_32x32x16_bf16 v[48:63], v[248:251], v[228:231], v[48:63]
	s_setprio 0
	ds_read_b64_tr_b16 v[228:229], v206 offset:16128
	ds_read_b64_tr_b16 v[230:231], v206 offset:17280
	ds_read_b64_tr_b16 v[242:243], v206 offset:17344
	ds_read_b64_tr_b16 v[240:241], v206 offset:16192
	s_setprio 0
	s_waitcnt lgkmcnt(6)
	v_mfma_f32_32x32x16_bf16 v[32:47], v[224:227], v[232:235], v[32:47]
	s_waitcnt lgkmcnt(4)
	v_mfma_f32_32x32x16_bf16 v[48:63], v[236:239], v[232:235], v[48:63]
	s_setprio 0
	s_setprio 0
	s_waitcnt lgkmcnt(2)
	v_mfma_f32_32x32x16_bf16 v[32:47], v[228:231], v[188:191], v[32:47]
	s_waitcnt lgkmcnt(0)
	v_mfma_f32_32x32x16_bf16 v[48:63], v[240:243], v[188:191], v[48:63]
	s_setprio 0
	v_readfirstlane_b32 vcc_lo, v200
	s_nop 1
	s_and_b32 vcc_lo, vcc_lo, 0x140
	s_bcnt1_i32_b32 vcc_lo, vcc_lo
	s_bitcmp1_b32 vcc_lo, 0
	s_cbranch_scc1 .Lns_td
	s_barrier
